# phase 5 row loop: lane-constant norm-weight vectors loaded once before the loop instead of per row
# baseline (speedup 1.0000x reference)
; DI float bflo(unsigned u) { return __uint_as_float(u << 16); }
; DI float bfhi(unsigned u) { return __uint_as_float(u & 0xffff0000u); }
; DI void finalize_phase(const Params& p) {
;     ...
;     bf16_t* O0 = (bf16_t*)(p.ws + OFF_A); const bf16_t* O1 = O0 + (size_t)NLAT * 1024; const bf16_t* P = (const bf16_t*)(p.ws + OFF_P) + (size_t)MTOT * P1W;
;     for (int row = gw; row < NLAT; row += NGW) {
; #pragma unroll
;         for (int part = 0; part < 2; ++part) {
;             const int col = 512 * part + 8 * lane;
;             const u32x4 a = *(const u32x4*)(O0 + (size_t)row * 1024 + col), bq = *(const u32x4*)(O1 + (size_t)row * 1024 + col);
;             const u32x4 gt = *(const u32x4*)(P + (size_t)row * P2W + (part ? 2048 : 0) + 8 * lane);
;             float o[8], g[8];
;             o[0] = bflo(a.x) + bflo(bq.x); o[1] = bfhi(a.x) + bfhi(bq.x); o[2] = bflo(a.y) + bflo(bq.y); o[3] = bfhi(a.y) + bfhi(bq.y);
;             o[4] = bflo(a.z) + bflo(bq.z); o[5] = bfhi(a.z) + bfhi(bq.z); o[6] = bflo(a.w) + bflo(bq.w); o[7] = bfhi(a.w) + bfhi(bq.w);
;             g[0] = bflo(gt.x); g[1] = bfhi(gt.x); g[2] = bflo(gt.y); g[3] = bfhi(gt.y); g[4] = bflo(gt.z); g[5] = bfhi(gt.z); g[6] = bflo(gt.w); g[7] = bfhi(gt.w);
;             float ss = 0.f;
; #pragma unroll
;             for (int e = 0; e < 8; ++e) ss += o[e] * o[e];
;             ss += __shfl_xor(ss, 1); ss += __shfl_xor(ss, 2); ss += __shfl_xor(ss, 4); ss += __shfl_xor(ss, 8);
;             const float rstd = rsqrtf(ss * (1.f / 128.f) + EPS);
;             const float* nw = part ? p.ml_norm + 8 * lane : p.dn_norm + ((8 * lane) & 127);
;             const f32x4 n0 = *(const f32x4*)nw, n1 = *(const f32x4*)(nw + 4);
.LBB0_650:
	s_cmp_lt_i32 s68, 6
	s_cselect_b64 s[4:5], -1, 0
	s_cmp_gt_i32 s69, 5
	s_cselect_b64 s[6:7], -1, 0
	s_and_b64 s[4:5], s[4:5], s[6:7]
	s_andn2_b64 vcc, exec, s[4:5]
	s_cbranch_vccnz .LBB0_708
	s_waitcnt lgkmcnt(0)
	s_load_dword s3, s[0:1], 0xb8
	v_lshl_add_u32 v8, s2, 3, v181
	s_add_u32 s6, s0, 0xb8
	s_mov_b32 s4, 0x10000
	s_addc_u32 s7, s1, 0
	v_cmp_gt_i32_e32 vcc, s4, v8
	s_and_saveexec_b64 s[8:9], vcc
	s_cbranch_execz .LBB0_654
	v_mbcnt_lo_u32_b32 v0, -1, 0
	v_mbcnt_hi_u32_b32 v0, -1, v0
	v_and_b32_e32 v2, 64, v0
	v_xor_b32_e32 v1, 1, v0
	v_add_u32_e32 v2, 64, v2
	v_cmp_lt_i32_e32 vcc, v1, v2
	v_mov_b32_e32 v11, 0
	s_waitcnt lgkmcnt(0)
	s_lshl_b32 s12, s3, 3
	v_cndmask_b32_e32 v1, v0, v1, vcc
	v_lshlrev_b32_e32 v21, 2, v1
	v_xor_b32_e32 v1, 2, v0
	v_cmp_lt_i32_e32 vcc, v1, v2
	v_ashrrev_i32_e32 v9, 31, v8
	s_movk_i32 s4, 0x1400
	v_cndmask_b32_e32 v1, v0, v1, vcc
	v_lshlrev_b32_e32 v26, 2, v1
	v_xor_b32_e32 v1, 4, v0
	v_cmp_lt_i32_e32 vcc, v1, v2
	s_ashr_i32 s13, s12, 31
	s_mul_i32 s14, s3, 0xa000
	v_cndmask_b32_e32 v1, v0, v1, vcc
	v_lshlrev_b32_e32 v27, 2, v1
	v_xor_b32_e32 v1, 8, v0
	v_cmp_lt_i32_e32 vcc, v1, v2
	s_mul_hi_i32 s15, s12, 0x1400
	s_lshl_b64 s[16:17], s[12:13], 11
	v_cndmask_b32_e32 v0, v0, v1, vcc
	v_lshlrev_b32_e32 v28, 2, v0
	v_lshlrev_b32_e32 v0, 5, v180
	v_and_b32_e32 v10, 0x1e0, v0
	v_lshl_add_u64 v[12:13], s[58:59], 0, v[10:11]
	v_and_b32_e32 v10, 0x7e0, v0
	v_and_b32_e32 v0, 63, v180
	v_lshl_add_u64 v[14:15], s[64:65], 0, v[10:11]
	v_lshlrev_b32_e32 v10, 4, v0
	v_mov_b64_e32 v[0:1], s[30:31]
	v_mad_i64_i32 v[16:17], s[4:5], v8, s4, v[0:1]
	v_lshlrev_b64 v[0:1], 11, v[8:9]
	v_lshl_add_u64 v[18:19], s[30:31], 0, v[0:1]
	s_mov_b64 s[18:19], 0
	s_brev_b32 s22, 60
	v_mov_b32_e32 v20, 0x358637bd
	s_mov_b32 s13, 0x800000
	s_mov_b32 s23, 0x1ef77000
	s_mov_b32 s24, 0xffff
	global_load_dwordx4 v[112:115], v[12:13], off offset:16
	global_load_dwordx4 v[116:119], v[12:13], off
	global_load_dwordx4 v[104:107], v[14:15], off
	global_load_dwordx4 v[108:111], v[14:15], off offset:16
	s_waitcnt vmcnt(0)
.LBB0_653:
	v_lshl_add_u64 v[38:39], v[18:19], 0, v[10:11]
	v_add_co_u32_e32 v22, vcc, 0x2376000, v38
	v_lshl_add_u64 v[24:25], v[16:17], 0, v[10:11]
	s_nop 0
	v_addc_co_u32_e32 v23, vcc, 0, v39, vcc
	v_add_co_u32_e32 v46, vcc, 0xa376000, v38
	v_add_co_u32_e64 v50, s[4:5], s23, v24
	s_nop 0
	v_addc_co_u32_e32 v47, vcc, 0, v39, vcc
	v_add_co_u32_e32 v24, vcc, 0x1ef76000, v24
	v_mov_b64_e32 v[0:1], v[112:113]
	v_mov_b64_e32 v[2:3], v[114:115]
	v_mov_b64_e32 v[4:5], v[116:117]
	v_mov_b64_e32 v[6:7], v[118:119]
	v_addc_co_u32_e64 v51, s[4:5], 0, v25, s[4:5]
	global_load_dwordx4 v[30:33], v[22:23], off
	global_load_dwordx4 v[34:37], v[22:23], off offset:1024
	global_load_dwordx4 v[38:41], v[46:47], off
	global_load_dwordx4 v[42:45], v[46:47], off offset:1024
	v_addc_co_u32_e32 v25, vcc, 0, v25, vcc
	global_load_dwordx4 v[46:49], v[24:25], off
	global_load_dwordx4 v[100:103], v[50:51], off
	v_add_u32_e32 v8, s12, v8
	v_lshl_add_u64 v[16:17], v[16:17], 0, s[14:15]
	v_lshl_add_u64 v[18:19], v[18:19], 0, s[16:17]
	s_waitcnt vmcnt(0)
	v_lshlrev_b32_e32 v24, 16, v33
	v_and_b32_e32 v25, 0xffff0000, v33
	v_lshlrev_b32_e32 v52, 16, v32
	v_and_b32_e32 v53, 0xffff0000, v32
	v_lshlrev_b32_e32 v32, 16, v31
	v_and_b32_e32 v33, 0xffff0000, v31
	v_lshlrev_b32_e32 v54, 16, v30
	v_and_b32_e32 v55, 0xffff0000, v30
	v_lshlrev_b32_e32 v30, 16, v37
	v_and_b32_e32 v31, 0xffff0000, v37
	v_lshlrev_b32_e32 v56, 16, v36
	v_and_b32_e32 v57, 0xffff0000, v36
	v_lshlrev_b32_e32 v36, 16, v35
	v_and_b32_e32 v37, 0xffff0000, v35
	v_lshlrev_b32_e32 v58, 16, v34
	v_and_b32_e32 v59, 0xffff0000, v34
	v_lshlrev_b32_e32 v34, 16, v41
	v_and_b32_e32 v35, 0xffff0000, v41
	v_lshlrev_b32_e32 v60, 16, v40
	v_and_b32_e32 v61, 0xffff0000, v40
	v_lshlrev_b32_e32 v40, 16, v39
	v_and_b32_e32 v41, 0xffff0000, v39
	v_lshlrev_b32_e32 v62, 16, v38
	v_and_b32_e32 v63, 0xffff0000, v38
	v_lshlrev_b32_e32 v38, 16, v45
	v_and_b32_e32 v39, 0xffff0000, v45
	v_lshlrev_b32_e32 v64, 16, v44
	v_and_b32_e32 v65, 0xffff0000, v44
	v_lshlrev_b32_e32 v44, 16, v43
	v_and_b32_e32 v45, 0xffff0000, v43
	v_lshlrev_b32_e32 v66, 16, v42
	v_and_b32_e32 v67, 0xffff0000, v42
	v_pk_add_f32 v[24:25], v[24:25], v[34:35]
	v_lshlrev_b32_e32 v34, 16, v49
	v_and_b32_e32 v35, 0xffff0000, v49
	v_pk_add_f32 v[42:43], v[52:53], v[60:61]
	v_lshlrev_b32_e32 v52, 16, v48
	v_and_b32_e32 v53, 0xffff0000, v48
	v_pk_add_f32 v[48:49], v[54:55], v[62:63]
	v_pk_add_f32 v[36:37], v[36:37], v[44:45]
	v_pk_add_f32 v[44:45], v[58:59], v[66:67]
	v_pk_add_f32 v[32:33], v[32:33], v[40:41]
	v_lshlrev_b32_e32 v40, 16, v47
	v_and_b32_e32 v41, 0xffff0000, v47
	v_lshlrev_b32_e32 v54, 16, v46
	v_and_b32_e32 v55, 0xffff0000, v46
	v_pk_add_f32 v[38:39], v[30:31], v[38:39]
	v_pk_add_f32 v[46:47], v[56:57], v[64:65]
	v_mov_b32_e32 v68, v45
	v_mov_b32_e32 v69, v49
	v_pk_mul_f32 v[30:31], v[24:25], v[24:25]
	v_pk_mul_f32 v[56:57], v[42:43], v[42:43]
	v_pk_mul_f32 v[58:59], v[32:33], v[32:33]
	v_mul_f32_e32 v70, 0xbfb8aa3b, v40
	v_mul_f32_e32 v71, 0xbfb8aa3b, v41
	v_pk_mul_f32 v[60:61], v[38:39], v[38:39]
	v_pk_mul_f32 v[62:63], v[46:47], v[46:47]
	v_pk_mul_f32 v[64:65], v[36:37], v[36:37]
	v_mov_b32_e32 v66, v44
	v_mov_b32_e32 v67, v48
	v_pk_mul_f32 v[68:69], v[68:69], v[68:69]
	v_exp_f32_e32 v76, v70
	v_exp_f32_e32 v77, v71
	v_mov_b32_e32 v70, v64
	v_mov_b32_e32 v71, v58
	v_mov_b32_e32 v58, v65
	v_mov_b32_e32 v64, v62
	v_mov_b32_e32 v65, v56
	v_mov_b32_e32 v56, v63
	v_mov_b32_e32 v62, v60
	v_mov_b32_e32 v63, v30
	v_mov_b32_e32 v30, v61
	v_pk_fma_f32 v[60:61], v[66:67], v[66:67], v[68:69]
	v_mul_f32_e32 v9, 0xbfb8aa3b, v52
	v_pk_add_f32 v[60:61], v[70:71], v[60:61]
	v_exp_f32_e32 v9, v9
	v_pk_add_f32 v[58:59], v[58:59], v[60:61]
	v_mul_f32_e32 v29, 0xbfb8aa3b, v53
	v_pk_add_f32 v[58:59], v[64:65], v[58:59]
	v_mul_f32_e32 v72, 0xbfb8aa3b, v54
	v_pk_add_f32 v[56:57], v[56:57], v[58:59]
	v_mul_f32_e32 v73, 0xbfb8aa3b, v55
	v_pk_add_f32 v[56:57], v[62:63], v[56:57]
	v_mul_f32_e32 v74, 0xbfb8aa3b, v34
	v_pk_add_f32 v[30:31], v[30:31], v[56:57]
	s_nop 1
	v_mov_b32_dpp v57, v31 quad_perm:[1,0,3,2] row_mask:0xf bank_mask:0xf
	s_nop 1
	v_mov_b32_dpp v56, v30 quad_perm:[1,0,3,2] row_mask:0xf bank_mask:0xf
	v_mul_f32_e32 v75, 0xbfb8aa3b, v35
	v_add_f32_e32 v9, 1.0, v9
	v_exp_f32_e32 v29, v29
	v_exp_f32_e32 v72, v72
	s_waitcnt lgkmcnt(0)
; DI unsigned pk2(float a, float b) { f32x2 v = {a, b}; bf16x2_t r = __builtin_convertvector(v, bf16x2_t); return __builtin_bit_cast(unsigned, r); }
; DI float sigmoidf_(float x) { return __builtin_amdgcn_rcpf(1.f + __expf(-x)); }
; DI float siluf_(float x) { return x * __builtin_amdgcn_rcpf(1.f + __expf(-x)); }
; DI void finalize_phase(const Params& p) {
;     ...
;             float ss = 0.f;
; #pragma unroll
;             for (int e = 0; e < 8; ++e) ss += o[e] * o[e];
;             ss += __shfl_xor(ss, 1); ss += __shfl_xor(ss, 2); ss += __shfl_xor(ss, 4); ss += __shfl_xor(ss, 8);
;             const float rstd = rsqrtf(ss * (1.f / 128.f) + EPS);
;             const float* nw = part ? p.ml_norm + 8 * lane : p.dn_norm + ((8 * lane) & 127);
;             const f32x4 n0 = *(const f32x4*)nw, n1 = *(const f32x4*)(nw + 4);
;             const float nn[8] = {n0.x, n0.y, n0.z, n0.w, n1.x, n1.y, n1.z, n1.w};
;             float y[8];
; #pragma unroll
;             for (int e = 0; e < 8; ++e) y[e] = o[e] * rstd * nn[e] * (part ? sigmoidf_(g[e]) : siluf_(g[e]));
;             u32x4 ov; ov.x = pk2(y[0], y[1]); ov.y = pk2(y[2], y[3]); ov.z = pk2(y[4], y[5]); ov.w = pk2(y[6], y[7]);
;             *(u32x4*)(O0 + (size_t)row * 1024 + col) = ov;
	v_pk_add_f32 v[30:31], v[30:31], v[56:57]
	s_nop 1
	v_mov_b32_dpp v57, v31 quad_perm:[2,3,0,1] row_mask:0xf bank_mask:0xf
	s_nop 1
	v_mov_b32_dpp v56, v30 quad_perm:[2,3,0,1] row_mask:0xf bank_mask:0xf
	v_exp_f32_e32 v73, v73
	v_exp_f32_e32 v74, v74
	v_exp_f32_e32 v75, v75
	v_rcp_f32_e32 v60, v9
	s_waitcnt lgkmcnt(0)
	v_pk_add_f32 v[30:31], v[30:31], v[56:57]
	s_nop 1
	v_mov_b32_dpp v57, v31 row_half_mirror row_mask:0xf bank_mask:0xf
	s_nop 1
	v_mov_b32_dpp v56, v30 row_half_mirror row_mask:0xf bank_mask:0xf
	v_add_f32_e32 v29, 1.0, v29
	v_add_f32_e32 v66, 1.0, v76
	v_add_f32_e32 v67, 1.0, v77
	v_add_f32_e32 v68, 1.0, v72
	s_waitcnt lgkmcnt(0)
	v_pk_add_f32 v[30:31], v[30:31], v[56:57]
	s_nop 1
	v_mov_b32_dpp v57, v31 row_ror:8 row_mask:0xf bank_mask:0xf
	s_nop 1
	v_mov_b32_dpp v56, v30 row_ror:8 row_mask:0xf bank_mask:0xf
	v_add_f32_e32 v69, 1.0, v73
	v_add_f32_e32 v70, 1.0, v74
	v_add_f32_e32 v71, 1.0, v75
	v_rcp_f32_e32 v61, v29
	s_waitcnt lgkmcnt(0)
	v_pk_add_f32 v[30:31], v[30:31], v[56:57]
	v_rcp_f32_e32 v64, v66
	v_pk_fma_f32 v[56:57], v[30:31], s[22:23], v[20:21] op_sel_hi:[1,0,0]
	v_rcp_f32_e32 v65, v67
	v_mul_f32_e32 v9, 0x4b800000, v57
	v_cmp_gt_f32_e32 vcc, s13, v57
	v_rcp_f32_e32 v66, v68
	v_rcp_f32_e32 v67, v69
	v_cndmask_b32_e32 v9, v57, v9, vcc
	v_rsq_f32_e32 v9, v9
	v_rcp_f32_e32 v68, v70
	v_rcp_f32_e32 v69, v71
	v_pk_mul_f32 v[52:53], v[60:61], v[52:53]
	v_mul_f32_e32 v29, 0x45800000, v9
	v_cndmask_b32_e32 v30, v9, v29, vcc
	v_pk_mul_f32 v[48:49], v[48:49], v[30:31] op_sel_hi:[1,0]
	v_pk_mul_f32 v[32:33], v[32:33], v[30:31] op_sel_hi:[1,0]
	v_pk_mul_f32 v[42:43], v[42:43], v[30:31] op_sel_hi:[1,0]
	v_pk_mul_f32 v[24:25], v[24:25], v[30:31] op_sel_hi:[1,0]
	v_pk_mul_f32 v[40:41], v[64:65], v[40:41]
	v_pk_mul_f32 v[54:55], v[66:67], v[54:55]
	v_pk_mul_f32 v[34:35], v[68:69], v[34:35]
	v_pk_mul_f32 v[4:5], v[4:5], v[48:49]
	v_pk_mul_f32 v[6:7], v[6:7], v[32:33]
	v_pk_mul_f32 v[0:1], v[0:1], v[42:43]
	v_pk_mul_f32 v[2:3], v[2:3], v[24:25]
	v_pk_mul_f32 v[4:5], v[54:55], v[4:5]
	v_pk_mul_f32 v[6:7], v[40:41], v[6:7]
	v_pk_mul_f32 v[24:25], v[52:53], v[0:1]
	v_pk_mul_f32 v[30:31], v[34:35], v[2:3]
	v_cvt_pk_bf16_f32 v0, v4, v5
	v_cvt_pk_bf16_f32 v1, v6, v7
	v_cvt_pk_bf16_f32 v2, v24, v25
	v_cvt_pk_bf16_f32 v3, v30, v31
	global_store_dwordx4 v[22:23], v[0:3], off
	s_nop 1
	v_mov_b64_e32 v[0:1], v[100:101]
	v_mov_b64_e32 v[2:3], v[102:103]
	v_mov_b64_e32 v[4:5], v[104:105]
	v_mov_b64_e32 v[6:7], v[106:107]
	v_mov_b64_e32 v[30:31], v[108:109]
	v_mov_b64_e32 v[32:33], v[110:111]
	s_nop 0
	v_cmp_lt_i32_e32 vcc, s24, v8
	s_or_b64 s[18:19], vcc, s[18:19]
	v_mul_f32_e32 v9, 0x4b800000, v56
	v_cmp_gt_f32_e32 vcc, s13, v56
	v_and_b32_e32 v29, 0xffff0000, v0
	s_nop 0
	v_cndmask_b32_e32 v9, v56, v9, vcc
	v_rsq_f32_e32 v9, v9
	v_lshlrev_b32_e32 v42, 16, v2
	v_and_b32_e32 v43, 0xffff0000, v2
	v_mul_f32_e32 v24, 0x45800000, v9
	v_cndmask_b32_e32 v24, v9, v24, vcc
	v_pk_mul_f32 v[34:35], v[44:45], v[24:25] op_sel_hi:[1,0]
	v_pk_mul_f32 v[36:37], v[36:37], v[24:25] op_sel_hi:[1,0]
	v_pk_mul_f32 v[40:41], v[46:47], v[24:25] op_sel_hi:[1,0]
	v_pk_mul_f32 v[24:25], v[38:39], v[24:25] op_sel_hi:[1,0]
	v_lshlrev_b32_e32 v9, 16, v0
	v_lshlrev_b32_e32 v38, 16, v1
	v_and_b32_e32 v39, 0xffff0000, v1
	v_lshlrev_b32_e32 v44, 16, v3
	v_and_b32_e32 v45, 0xffff0000, v3
	v_pk_mul_f32 v[0:1], v[4:5], v[34:35]
	v_pk_mul_f32 v[2:3], v[6:7], v[36:37]
	v_pk_mul_f32 v[4:5], v[30:31], v[40:41]
	v_pk_mul_f32 v[6:7], v[32:33], v[24:25]
	v_mul_f32_e32 v9, 0xbfb8aa3b, v9
	v_mul_f32_e32 v24, 0xbfb8aa3b, v29
	v_mul_f32_e32 v25, 0xbfb8aa3b, v38
	v_mul_f32_e32 v29, 0xbfb8aa3b, v39
	v_mul_f32_e32 v30, 0xbfb8aa3b, v42
	v_mul_f32_e32 v31, 0xbfb8aa3b, v43
	v_mul_f32_e32 v32, 0xbfb8aa3b, v44
	v_mul_f32_e32 v33, 0xbfb8aa3b, v45
	v_exp_f32_e32 v9, v9
	v_exp_f32_e32 v24, v24
	v_exp_f32_e32 v25, v25
	v_exp_f32_e32 v29, v29
	v_exp_f32_e32 v30, v30
	v_exp_f32_e32 v31, v31
	v_exp_f32_e32 v32, v32
	v_exp_f32_e32 v33, v33
	v_add_f32_e32 v9, 1.0, v9
	v_add_f32_e32 v34, 1.0, v24
	v_add_f32_e32 v35, 1.0, v25
	v_add_f32_e32 v29, 1.0, v29
	v_add_f32_e32 v36, 1.0, v30
	v_add_f32_e32 v37, 1.0, v31
	v_add_f32_e32 v38, 1.0, v32
	v_add_f32_e32 v39, 1.0, v33
	v_rcp_f32_e32 v24, v9
	v_rcp_f32_e32 v25, v34
	v_rcp_f32_e32 v30, v35
	v_rcp_f32_e32 v31, v29
	v_rcp_f32_e32 v32, v36
	v_rcp_f32_e32 v33, v37
	v_rcp_f32_e32 v34, v38
	v_rcp_f32_e32 v35, v39
	v_pk_mul_f32 v[0:1], v[24:25], v[0:1]
	v_pk_mul_f32 v[2:3], v[30:31], v[2:3]
	v_pk_mul_f32 v[4:5], v[32:33], v[4:5]
	v_pk_mul_f32 v[6:7], v[34:35], v[6:7]
	v_cvt_pk_bf16_f32 v0, v0, v1
	v_cvt_pk_bf16_f32 v1, v2, v3
	v_cvt_pk_bf16_f32 v2, v4, v5
	v_cvt_pk_bf16_f32 v3, v6, v7
	global_store_dwordx4 v[22:23], v[0:3], off offset:1024
	s_andn2_b64 exec, exec, s[18:19]
	s_cbranch_execnz .LBB0_653
